# non-temporal hint on the MLP-up output stores (268 MB stream) to keep the f32 residual in the memory-side cache
# baseline (speedup 1.0000x reference)
; DEVI unsigned pk2(float lo, float hi) { unsigned r; asm("v_cvt_pk_bf16_f32 %0, %1, %2" : "=v"(r) : "v"(lo), "v"(hi)); return r; }
;   DEVI void operator()(const f32x4 (&acc)[2][2][4][2], const pg8::Unit& u, int wr, int wc, int fr, int fq) const {
;     ...
;       for (int m = 0; m < 4; ++m) {
;         const int row = u.pm * 256 + ai * 128 + wr * 64 + m * 16 + fr;
;         const float4* sp = (const float4*)(ssrow + (size_t)row * 16);
;         const float4 a = sp[0], b = sp[1], c = sp[2], d = sp[3];
;         const float ssum = (((a.x + a.y) + (a.z + a.w)) + ((b.x + b.y) + (b.z + b.w))) + (((c.x + c.y) + (c.z + c.w)) + ((d.x + d.y) + (d.z + d.w)));
;         const float rs = rsqrtf(ssum * (1.f / 1024.f) + 1e-6f);
; #pragma unroll
;         for (int bj = 0; bj < 2; ++bj) {
;           const int col = u.pn * 256 + bj * 128 + wc * 32 + fq * 8;
;           float h[8];
; #pragma unroll
;           for (int j = 0; j < 4; ++j) { const float h0 = fmaxf(acc[ai][bj][m][0][j] * rs, 0.f), h1 = fmaxf(acc[ai][bj][m][1][j] * rs, 0.f); h[j] = h0 * h0; h[4 + j] = h1 * h1; }
;           u32x4 w; w.x = pk2(h[0], h[1]); w.y = pk2(h[2], h[3]); w.z = pk2(h[4], h[5]); w.w = pk2(h[6], h[7]);
;           *(u32x4*)(uo + (size_t)row * DFF + col) = w;
.LBB0_1974:
	v_lshl_add_u32 v146, s3, 8, v131
	v_ashrrev_i32_e32 v147, 31, v146
	v_lshlrev_b64 v[132:133], 6, v[146:147]
	v_lshl_add_u64 v[162:163], s[54:55], 0, v[132:133]
	global_load_dwordx4 v[132:135], v[162:163], off offset:48
	global_load_dwordx4 v[154:157], v[162:163], off offset:16
	global_load_dwordx4 v[158:161], v[162:163], off offset:32
	s_nop 0
	global_load_dwordx4 v[162:165], v[162:163], off
	v_lshl_or_b32 v148, s2, 8, v151
	v_readlane_b32 s24, v252, 40
	v_readlane_b32 s26, v252, 42
	v_readlane_b32 s27, v252, 43
	v_ashrrev_i32_e32 v149, 31, v148
	s_mov_b64 s[22:23], -1
	v_readlane_b32 s25, v252, 41
	s_waitcnt vmcnt(0)
	v_mov_b32_e32 v167, v158
	v_mov_b32_e32 v166, v162
	v_mov_b32_e32 v158, v163
	v_mov_b32_e32 v162, v164
	v_mov_b32_e32 v163, v160
	v_mov_b32_e32 v160, v165
	v_pk_add_f32 v[158:159], v[166:167], v[158:159]
	v_pk_add_f32 v[160:161], v[162:163], v[160:161]
	s_nop 0
	v_pk_add_f32 v[158:159], v[158:159], v[160:161]
	v_mov_b32_e32 v160, v154
	v_mov_b32_e32 v161, v132
	v_mov_b32_e32 v132, v155
	v_mov_b32_e32 v154, v156
	v_mov_b32_e32 v155, v134
	v_mov_b32_e32 v134, v157
	v_pk_add_f32 v[132:133], v[160:161], v[132:133]
	v_pk_add_f32 v[134:135], v[154:155], v[134:135]
	s_nop 0
	v_pk_add_f32 v[132:133], v[132:133], v[134:135]
	s_nop 0
	v_pk_add_f32 v[132:133], v[158:159], v[132:133]
	s_nop 0
	v_add_f32_e32 v132, v132, v133
	v_fmamk_f32 v132, v132, 0x3a800000, v224
	v_cmp_gt_f32_e32 vcc, s77, v132
	v_mul_f32_e32 v133, 0x4b800000, v132
	s_nop 0
	v_cndmask_b32_e32 v132, v132, v133, vcc
	v_rsq_f32_e32 v132, v132
	s_nop 0
	v_mul_f32_e32 v133, 0x45800000, v132
	v_cndmask_b32_e32 v134, v132, v133, vcc
	v_mul_f32_e32 v122, v122, v134
	v_mul_f32_e32 v123, v123, v134
	v_mul_f32_e32 v124, v124, v134
	v_max_f32_e32 v122, 0, v122
	v_max_f32_e32 v123, 0, v123
	v_max_f32_e32 v124, 0, v124
	v_mul_f32_e32 v126, v126, v134
	v_mul_f32_e32 v135, v122, v122
	v_mul_f32_e32 v122, v127, v134
	v_mul_f32_e32 v127, v123, v123
	v_mul_f32_e32 v123, v128, v134
	v_mul_f32_e32 v128, v124, v124
	v_mul_f32_e32 v124, v129, v134
	v_mul_f32_e32 v125, v125, v134
	v_max_f32_e32 v126, 0, v126
	v_max_f32_e32 v122, 0, v122
	v_max_f32_e32 v123, 0, v123
	v_max_f32_e32 v124, 0, v124
	v_max_f32_e32 v125, 0, v125
	v_lshlrev_b64 v[132:133], 13, v[146:147]
	v_mul_f32_e32 v126, v126, v126
	v_mul_f32_e32 v122, v122, v122
	v_mul_f32_e32 v123, v123, v123
	v_mul_f32_e32 v124, v124, v124
	v_mul_f32_e32 v125, v125, v125
	v_cvt_pk_bf16_f32 v122, v126, v122
	v_cvt_pk_bf16_f32 v123, v123, v124
	v_cvt_pk_bf16_f32 v124, v135, v127
	v_cvt_pk_bf16_f32 v125, v128, v125
	v_lshl_add_u64 v[128:129], s[26:27], 0, v[132:133]
	v_lshlrev_b64 v[126:127], 1, v[148:149]
	v_mul_f32_e32 v114, v114, v134
	v_mul_f32_e32 v115, v115, v134
	v_mul_f32_e32 v116, v116, v134
	v_lshl_add_u64 v[128:129], v[128:129], 0, v[126:127]
	v_max_f32_e32 v114, 0, v114
	v_max_f32_e32 v115, 0, v115
	v_max_f32_e32 v116, 0, v116
	global_store_dwordx4 v[128:129], v[122:125], off nt
	v_mul_f32_e32 v117, v117, v134
	v_mul_f32_e32 v118, v118, v134
	v_mul_f32_e32 v122, v114, v114
	v_mul_f32_e32 v114, v119, v134
	v_mul_f32_e32 v119, v115, v115
	v_mul_f32_e32 v115, v120, v134
	v_mul_f32_e32 v120, v116, v116
	v_mul_f32_e32 v116, v121, v134
	v_max_f32_e32 v114, 0, v114
	v_max_f32_e32 v115, 0, v115
	v_max_f32_e32 v116, 0, v116
	v_max_f32_e32 v117, 0, v117
	v_max_f32_e32 v118, 0, v118
	v_mul_f32_e32 v114, v114, v114
	v_mul_f32_e32 v115, v115, v115
	v_mul_f32_e32 v116, v116, v116
	v_mul_f32_e32 v117, v117, v117
	v_mul_f32_e32 v118, v118, v118
	v_cvt_pk_bf16_f32 v114, v118, v114
	v_cvt_pk_bf16_f32 v115, v115, v116
	v_cvt_pk_bf16_f32 v116, v122, v119
	v_cvt_pk_bf16_f32 v117, v120, v117
	global_store_dwordx4 v[128:129], v[114:117], off offset:256 nt
	v_or_b32_e32 v128, 16, v146
	v_ashrrev_i32_e32 v129, 31, v128
	v_lshlrev_b64 v[114:115], 6, v[128:129]
	v_lshl_add_u64 v[148:149], s[54:55], 0, v[114:115]
	global_load_dwordx4 v[114:117], v[148:149], off offset:48
	global_load_dwordx4 v[118:121], v[148:149], off offset:16
	global_load_dwordx4 v[122:125], v[148:149], off offset:32
	global_load_dwordx4 v[132:135], v[148:149], off
	s_waitcnt vmcnt(1)
	v_mov_b32_e32 v149, v122
	s_waitcnt vmcnt(0)
	v_mov_b32_e32 v148, v132
	v_mov_b32_e32 v122, v133
	v_mov_b32_e32 v132, v134
	v_mov_b32_e32 v133, v124
	v_mov_b32_e32 v124, v135
	v_pk_add_f32 v[122:123], v[148:149], v[122:123]
	v_pk_add_f32 v[124:125], v[132:133], v[124:125]
	s_nop 0
	v_pk_add_f32 v[122:123], v[122:123], v[124:125]
	v_mov_b32_e32 v124, v118
	v_mov_b32_e32 v125, v114
	v_mov_b32_e32 v114, v119
	v_mov_b32_e32 v118, v120
	v_mov_b32_e32 v119, v116
	v_mov_b32_e32 v116, v121
	v_pk_add_f32 v[114:115], v[124:125], v[114:115]
	v_pk_add_f32 v[116:117], v[118:119], v[116:117]
	s_nop 0
	v_pk_add_f32 v[114:115], v[114:115], v[116:117]
	s_nop 0
	v_pk_add_f32 v[114:115], v[122:123], v[114:115]
	s_nop 0
	v_add_f32_e32 v114, v114, v115
	v_fmamk_f32 v114, v114, 0x3a800000, v224
	v_cmp_gt_f32_e32 vcc, s77, v114
	v_mul_f32_e32 v115, 0x4b800000, v114
	s_nop 0
	v_cndmask_b32_e32 v114, v114, v115, vcc
	v_rsq_f32_e32 v114, v114
	s_nop 0
	v_mul_f32_e32 v115, 0x45800000, v114
	v_cndmask_b32_e32 v116, v114, v115, vcc
	v_mul_f32_e32 v106, v106, v116
	v_mul_f32_e32 v107, v107, v116
	v_mul_f32_e32 v108, v108, v116
	v_max_f32_e32 v106, 0, v106
	v_max_f32_e32 v107, 0, v107
	v_max_f32_e32 v108, 0, v108
	v_mul_f32_e32 v110, v110, v116
	v_mul_f32_e32 v117, v106, v106
	v_mul_f32_e32 v106, v111, v116
	v_mul_f32_e32 v111, v107, v107
	v_mul_f32_e32 v107, v112, v116
	v_mul_f32_e32 v112, v108, v108
	v_mul_f32_e32 v108, v113, v116
	v_max_f32_e32 v110, 0, v110
	v_max_f32_e32 v106, 0, v106
	v_max_f32_e32 v107, 0, v107
; DEVI unsigned pk2(float lo, float hi) { unsigned r; asm("v_cvt_pk_bf16_f32 %0, %1, %2" : "=v"(r) : "v"(lo), "v"(hi)); return r; }
;   DEVI void operator()(const f32x4 (&acc)[2][2][4][2], const pg8::Unit& u, int wr, int wc, int fr, int fq) const {
;     ...
;       for (int m = 0; m < 4; ++m) {
;         const int row = u.pm * 256 + ai * 128 + wr * 64 + m * 16 + fr;
;         const float4* sp = (const float4*)(ssrow + (size_t)row * 16);
;         const float4 a = sp[0], b = sp[1], c = sp[2], d = sp[3];
;         const float ssum = (((a.x + a.y) + (a.z + a.w)) + ((b.x + b.y) + (b.z + b.w))) + (((c.x + c.y) + (c.z + c.w)) + ((d.x + d.y) + (d.z + d.w)));
;         const float rs = rsqrtf(ssum * (1.f / 1024.f) + 1e-6f);
; #pragma unroll
;         for (int bj = 0; bj < 2; ++bj) {
;           const int col = u.pn * 256 + bj * 128 + wc * 32 + fq * 8;
;           float h[8];
; #pragma unroll
;           for (int j = 0; j < 4; ++j) { const float h0 = fmaxf(acc[ai][bj][m][0][j] * rs, 0.f), h1 = fmaxf(acc[ai][bj][m][1][j] * rs, 0.f); h[j] = h0 * h0; h[4 + j] = h1 * h1; }
;           u32x4 w; w.x = pk2(h[0], h[1]); w.y = pk2(h[2], h[3]); w.z = pk2(h[4], h[5]); w.w = pk2(h[6], h[7]);
;           *(u32x4*)(uo + (size_t)row * DFF + col) = w;
	v_max_f32_e32 v108, 0, v108
	v_lshlrev_b64 v[114:115], 13, v[128:129]
	v_mul_f32_e32 v110, v110, v110
	v_mul_f32_e32 v106, v106, v106
	v_mul_f32_e32 v107, v107, v107
	v_mul_f32_e32 v109, v109, v116
	v_mul_f32_e32 v108, v108, v108
	v_max_f32_e32 v109, 0, v109
	v_cvt_pk_bf16_f32 v106, v110, v106
	v_cvt_pk_bf16_f32 v107, v107, v108
	v_cvt_pk_bf16_f32 v108, v117, v111
	v_lshl_add_u64 v[110:111], s[26:27], 0, v[114:115]
	v_mul_f32_e32 v98, v98, v116
	v_mul_f32_e32 v99, v99, v116
	v_mul_f32_e32 v100, v100, v116
	v_mul_f32_e32 v109, v109, v109
	v_lshl_add_u64 v[110:111], v[110:111], 0, v[126:127]
	v_max_f32_e32 v98, 0, v98
	v_max_f32_e32 v99, 0, v99
	v_max_f32_e32 v100, 0, v100
	v_cvt_pk_bf16_f32 v109, v112, v109
	global_store_dwordx4 v[110:111], v[106:109], off nt
	v_mul_f32_e32 v101, v101, v116
	v_mul_f32_e32 v102, v102, v116
	v_mul_f32_e32 v106, v98, v98
	v_mul_f32_e32 v98, v103, v116
	v_mul_f32_e32 v103, v99, v99
	v_mul_f32_e32 v99, v104, v116
	v_mul_f32_e32 v104, v100, v100
	v_mul_f32_e32 v100, v105, v116
	v_max_f32_e32 v98, 0, v98
	v_max_f32_e32 v99, 0, v99
	v_max_f32_e32 v100, 0, v100
	v_max_f32_e32 v101, 0, v101
	v_max_f32_e32 v102, 0, v102
	v_mul_f32_e32 v98, v98, v98
	v_mul_f32_e32 v99, v99, v99
	v_mul_f32_e32 v100, v100, v100
	v_mul_f32_e32 v101, v101, v101
	v_mul_f32_e32 v102, v102, v102
	v_cvt_pk_bf16_f32 v98, v102, v98
	v_cvt_pk_bf16_f32 v99, v99, v100
	v_cvt_pk_bf16_f32 v100, v106, v103
	v_cvt_pk_bf16_f32 v101, v104, v101
	global_store_dwordx4 v[110:111], v[98:101], off offset:256 nt
	v_or_b32_e32 v110, 32, v146
	v_ashrrev_i32_e32 v111, 31, v110
	v_lshlrev_b64 v[98:99], 6, v[110:111]
	v_lshl_add_u64 v[112:113], s[54:55], 0, v[98:99]
	global_load_dwordx4 v[98:101], v[112:113], off offset:48
	global_load_dwordx4 v[102:105], v[112:113], off offset:16
	global_load_dwordx4 v[106:109], v[112:113], off offset:32
	s_nop 0
	global_load_dwordx4 v[112:115], v[112:113], off
	s_waitcnt vmcnt(1)
	v_mov_b32_e32 v117, v106
	s_waitcnt vmcnt(0)
	v_mov_b32_e32 v116, v112
	v_mov_b32_e32 v106, v113
	v_mov_b32_e32 v112, v114
	v_mov_b32_e32 v113, v108
	v_mov_b32_e32 v108, v115
	v_pk_add_f32 v[106:107], v[116:117], v[106:107]
	v_pk_add_f32 v[108:109], v[112:113], v[108:109]
	s_nop 0
	v_pk_add_f32 v[106:107], v[106:107], v[108:109]
	v_mov_b32_e32 v108, v102
	v_mov_b32_e32 v109, v98
	v_mov_b32_e32 v98, v103
	v_mov_b32_e32 v102, v104
	v_mov_b32_e32 v103, v100
	v_mov_b32_e32 v100, v105
	v_pk_add_f32 v[98:99], v[108:109], v[98:99]
	v_pk_add_f32 v[100:101], v[102:103], v[100:101]
	s_nop 0
	v_pk_add_f32 v[98:99], v[98:99], v[100:101]
	s_nop 0
	v_pk_add_f32 v[98:99], v[106:107], v[98:99]
	s_nop 0
	v_add_f32_e32 v98, v98, v99
	v_fmamk_f32 v98, v98, 0x3a800000, v224
	v_cmp_gt_f32_e32 vcc, s77, v98
	v_mul_f32_e32 v99, 0x4b800000, v98
	s_nop 0
	v_cndmask_b32_e32 v98, v98, v99, vcc
	v_rsq_f32_e32 v98, v98
	s_nop 0
	v_mul_f32_e32 v99, 0x45800000, v98
	v_cndmask_b32_e32 v100, v98, v99, vcc
	v_mul_f32_e32 v90, v90, v100
	v_mul_f32_e32 v91, v91, v100
	v_mul_f32_e32 v92, v92, v100
	v_max_f32_e32 v90, 0, v90
	v_max_f32_e32 v91, 0, v91
	v_max_f32_e32 v92, 0, v92
	v_mul_f32_e32 v94, v94, v100
	v_mul_f32_e32 v101, v90, v90
	v_mul_f32_e32 v90, v95, v100
	v_mul_f32_e32 v95, v91, v91
	v_mul_f32_e32 v91, v96, v100
	v_mul_f32_e32 v96, v92, v92
	v_mul_f32_e32 v92, v97, v100
	v_max_f32_e32 v94, 0, v94
	v_max_f32_e32 v90, 0, v90
	v_max_f32_e32 v91, 0, v91
	v_max_f32_e32 v92, 0, v92
	v_lshlrev_b64 v[98:99], 13, v[110:111]
	v_mul_f32_e32 v94, v94, v94
	v_mul_f32_e32 v90, v90, v90
	v_mul_f32_e32 v91, v91, v91
	v_mul_f32_e32 v93, v93, v100
	v_mul_f32_e32 v92, v92, v92
	v_max_f32_e32 v93, 0, v93
	v_cvt_pk_bf16_f32 v90, v94, v90
	v_cvt_pk_bf16_f32 v91, v91, v92
	v_cvt_pk_bf16_f32 v92, v101, v95
	v_lshl_add_u64 v[94:95], s[26:27], 0, v[98:99]
	v_mul_f32_e32 v82, v82, v100
	v_mul_f32_e32 v83, v83, v100
	v_mul_f32_e32 v84, v84, v100
	v_mul_f32_e32 v93, v93, v93
	v_lshl_add_u64 v[94:95], v[94:95], 0, v[126:127]
	v_max_f32_e32 v82, 0, v82
	v_max_f32_e32 v83, 0, v83
	v_max_f32_e32 v84, 0, v84
	v_cvt_pk_bf16_f32 v93, v96, v93
	global_store_dwordx4 v[94:95], v[90:93], off nt
	v_mul_f32_e32 v85, v85, v100
	v_mul_f32_e32 v86, v86, v100
	v_mul_f32_e32 v90, v82, v82
	v_mul_f32_e32 v82, v87, v100
	v_mul_f32_e32 v87, v83, v83
	v_mul_f32_e32 v83, v88, v100
	v_mul_f32_e32 v88, v84, v84
	v_mul_f32_e32 v84, v89, v100
	v_max_f32_e32 v82, 0, v82
	v_max_f32_e32 v83, 0, v83
	v_max_f32_e32 v84, 0, v84
	v_max_f32_e32 v85, 0, v85
	v_max_f32_e32 v86, 0, v86
	v_mul_f32_e32 v82, v82, v82
	v_mul_f32_e32 v83, v83, v83
	v_mul_f32_e32 v84, v84, v84
	v_mul_f32_e32 v85, v85, v85
	v_mul_f32_e32 v86, v86, v86
	v_cvt_pk_bf16_f32 v82, v86, v82
	v_cvt_pk_bf16_f32 v83, v83, v84
	v_cvt_pk_bf16_f32 v84, v90, v87
	v_cvt_pk_bf16_f32 v85, v88, v85
	global_store_dwordx4 v[94:95], v[82:85], off offset:256 nt
	v_or_b32_e32 v94, 48, v146
	v_ashrrev_i32_e32 v95, 31, v94
	v_lshlrev_b64 v[82:83], 6, v[94:95]
	v_lshl_add_u64 v[96:97], s[54:55], 0, v[82:83]
	global_load_dwordx4 v[82:85], v[96:97], off offset:48
	global_load_dwordx4 v[86:89], v[96:97], off offset:16
	global_load_dwordx4 v[90:93], v[96:97], off offset:32
	s_nop 0
	global_load_dwordx4 v[96:99], v[96:97], off
	s_waitcnt vmcnt(1)
	v_mov_b32_e32 v101, v90
	s_waitcnt vmcnt(0)
; DEVI unsigned pk2(float lo, float hi) { unsigned r; asm("v_cvt_pk_bf16_f32 %0, %1, %2" : "=v"(r) : "v"(lo), "v"(hi)); return r; }
;   DEVI void operator()(const f32x4 (&acc)[2][2][4][2], const pg8::Unit& u, int wr, int wc, int fr, int fq) const {
;     ...
;       for (int m = 0; m < 4; ++m) {
;         const int row = u.pm * 256 + ai * 128 + wr * 64 + m * 16 + fr;
;         const float4* sp = (const float4*)(ssrow + (size_t)row * 16);
;         const float4 a = sp[0], b = sp[1], c = sp[2], d = sp[3];
;         const float ssum = (((a.x + a.y) + (a.z + a.w)) + ((b.x + b.y) + (b.z + b.w))) + (((c.x + c.y) + (c.z + c.w)) + ((d.x + d.y) + (d.z + d.w)));
;         const float rs = rsqrtf(ssum * (1.f / 1024.f) + 1e-6f);
; #pragma unroll
;         for (int bj = 0; bj < 2; ++bj) {
;           const int col = u.pn * 256 + bj * 128 + wc * 32 + fq * 8;
;           float h[8];
; #pragma unroll
;           for (int j = 0; j < 4; ++j) { const float h0 = fmaxf(acc[ai][bj][m][0][j] * rs, 0.f), h1 = fmaxf(acc[ai][bj][m][1][j] * rs, 0.f); h[j] = h0 * h0; h[4 + j] = h1 * h1; }
;           u32x4 w; w.x = pk2(h[0], h[1]); w.y = pk2(h[2], h[3]); w.z = pk2(h[4], h[5]); w.w = pk2(h[6], h[7]);
;           *(u32x4*)(uo + (size_t)row * DFF + col) = w;
	v_mov_b32_e32 v100, v96
	v_mov_b32_e32 v90, v97
	v_mov_b32_e32 v96, v98
	v_mov_b32_e32 v97, v92
	v_mov_b32_e32 v92, v99
	v_pk_add_f32 v[90:91], v[100:101], v[90:91]
	v_pk_add_f32 v[92:93], v[96:97], v[92:93]
	s_nop 0
	v_pk_add_f32 v[90:91], v[90:91], v[92:93]
	v_mov_b32_e32 v92, v86
	v_mov_b32_e32 v93, v82
	v_mov_b32_e32 v82, v87
	v_mov_b32_e32 v86, v88
	v_mov_b32_e32 v87, v84
	v_mov_b32_e32 v84, v89
	v_pk_add_f32 v[82:83], v[92:93], v[82:83]
	v_pk_add_f32 v[84:85], v[86:87], v[84:85]
	s_nop 0
	v_pk_add_f32 v[82:83], v[82:83], v[84:85]
	s_nop 0
	v_pk_add_f32 v[82:83], v[90:91], v[82:83]
	s_nop 0
	v_add_f32_e32 v82, v82, v83
	v_fmamk_f32 v82, v82, 0x3a800000, v224
	v_cmp_gt_f32_e32 vcc, s77, v82
	v_mul_f32_e32 v83, 0x4b800000, v82
	s_nop 0
	v_cndmask_b32_e32 v82, v82, v83, vcc
	v_rsq_f32_e32 v82, v82
	s_nop 0
	v_mul_f32_e32 v83, 0x45800000, v82
	v_cndmask_b32_e32 v84, v82, v83, vcc
	v_mul_f32_e32 v74, v74, v84
	v_mul_f32_e32 v75, v75, v84
	v_mul_f32_e32 v76, v76, v84
	v_max_f32_e32 v74, 0, v74
	v_max_f32_e32 v75, 0, v75
	v_max_f32_e32 v76, 0, v76
	v_mul_f32_e32 v78, v78, v84
	v_mul_f32_e32 v85, v74, v74
	v_mul_f32_e32 v74, v79, v84
	v_mul_f32_e32 v79, v75, v75
	v_mul_f32_e32 v75, v80, v84
	v_mul_f32_e32 v80, v76, v76
	v_mul_f32_e32 v76, v81, v84
	v_max_f32_e32 v78, 0, v78
	v_max_f32_e32 v74, 0, v74
	v_max_f32_e32 v75, 0, v75
	v_max_f32_e32 v76, 0, v76
	v_lshlrev_b64 v[82:83], 13, v[94:95]
	v_mul_f32_e32 v78, v78, v78
	v_mul_f32_e32 v74, v74, v74
	v_mul_f32_e32 v75, v75, v75
	v_mul_f32_e32 v77, v77, v84
	v_mul_f32_e32 v76, v76, v76
	v_max_f32_e32 v77, 0, v77
	v_cvt_pk_bf16_f32 v74, v78, v74
	v_cvt_pk_bf16_f32 v75, v75, v76
	v_cvt_pk_bf16_f32 v76, v85, v79
	v_lshl_add_u64 v[78:79], s[26:27], 0, v[82:83]
	v_mul_f32_e32 v66, v66, v84
	v_mul_f32_e32 v67, v67, v84
	v_mul_f32_e32 v68, v68, v84
	v_mul_f32_e32 v77, v77, v77
	v_lshl_add_u64 v[78:79], v[78:79], 0, v[126:127]
	v_max_f32_e32 v66, 0, v66
	v_max_f32_e32 v67, 0, v67
	v_max_f32_e32 v68, 0, v68
	v_cvt_pk_bf16_f32 v77, v80, v77
	global_store_dwordx4 v[78:79], v[74:77], off nt
	v_mul_f32_e32 v69, v69, v84
	v_mul_f32_e32 v70, v70, v84
	v_mul_f32_e32 v74, v66, v66
	v_mul_f32_e32 v66, v71, v84
	v_mul_f32_e32 v71, v67, v67
	v_mul_f32_e32 v67, v72, v84
	v_mul_f32_e32 v72, v68, v68
	v_mul_f32_e32 v68, v73, v84
	v_max_f32_e32 v66, 0, v66
	v_max_f32_e32 v67, 0, v67
	v_max_f32_e32 v68, 0, v68
	v_max_f32_e32 v69, 0, v69
	v_max_f32_e32 v70, 0, v70
	v_mul_f32_e32 v66, v66, v66
	v_mul_f32_e32 v67, v67, v67
	v_mul_f32_e32 v68, v68, v68
	v_mul_f32_e32 v69, v69, v69
	v_mul_f32_e32 v70, v70, v70
	v_cvt_pk_bf16_f32 v66, v70, v66
	v_cvt_pk_bf16_f32 v67, v67, v68
	v_cvt_pk_bf16_f32 v68, v74, v71
	v_cvt_pk_bf16_f32 v69, v72, v69
	global_store_dwordx4 v[78:79], v[66:69], off offset:256 nt
	v_add_u32_e32 v78, 0x80, v146
	v_ashrrev_i32_e32 v79, 31, v78
	v_lshlrev_b64 v[66:67], 6, v[78:79]
	v_lshl_add_u64 v[80:81], s[54:55], 0, v[66:67]
	global_load_dwordx4 v[66:69], v[80:81], off offset:48
	global_load_dwordx4 v[70:73], v[80:81], off offset:16
	global_load_dwordx4 v[74:77], v[80:81], off offset:32
	s_nop 0
	global_load_dwordx4 v[80:83], v[80:81], off
	s_waitcnt vmcnt(1)
	v_mov_b32_e32 v85, v74
	s_waitcnt vmcnt(0)
	v_mov_b32_e32 v84, v80
	v_mov_b32_e32 v74, v81
	v_mov_b32_e32 v80, v82
	v_mov_b32_e32 v81, v76
	v_mov_b32_e32 v76, v83
	v_pk_add_f32 v[74:75], v[84:85], v[74:75]
	v_pk_add_f32 v[76:77], v[80:81], v[76:77]
	s_nop 0
	v_pk_add_f32 v[74:75], v[74:75], v[76:77]
	v_mov_b32_e32 v76, v70
	v_mov_b32_e32 v77, v66
	v_mov_b32_e32 v66, v71
	v_mov_b32_e32 v70, v72
	v_mov_b32_e32 v71, v68
	v_mov_b32_e32 v68, v73
	v_pk_add_f32 v[66:67], v[76:77], v[66:67]
	v_pk_add_f32 v[68:69], v[70:71], v[68:69]
	s_nop 0
	v_pk_add_f32 v[66:67], v[66:67], v[68:69]
	s_nop 0
	v_pk_add_f32 v[66:67], v[74:75], v[66:67]
	s_nop 0
	v_add_f32_e32 v66, v66, v67
	v_fmamk_f32 v66, v66, 0x3a800000, v224
	v_cmp_gt_f32_e32 vcc, s77, v66
	v_mul_f32_e32 v67, 0x4b800000, v66
	s_nop 0
	v_cndmask_b32_e32 v66, v66, v67, vcc
	v_rsq_f32_e32 v66, v66
	s_nop 0
	v_mul_f32_e32 v67, 0x45800000, v66
	v_cndmask_b32_e32 v68, v66, v67, vcc
	v_mul_f32_e32 v58, v58, v68
	v_mul_f32_e32 v59, v59, v68
	v_mul_f32_e32 v60, v60, v68
	v_max_f32_e32 v58, 0, v58
	v_max_f32_e32 v59, 0, v59
	v_max_f32_e32 v60, 0, v60
	v_mul_f32_e32 v62, v62, v68
	v_mul_f32_e32 v69, v58, v58
	v_mul_f32_e32 v58, v63, v68
	v_mul_f32_e32 v63, v59, v59
	v_mul_f32_e32 v59, v64, v68
	v_mul_f32_e32 v64, v60, v60
	v_mul_f32_e32 v60, v65, v68
	v_max_f32_e32 v62, 0, v62
	v_max_f32_e32 v58, 0, v58
	v_max_f32_e32 v59, 0, v59
	v_max_f32_e32 v60, 0, v60
	v_lshlrev_b64 v[66:67], 13, v[78:79]
	v_mul_f32_e32 v62, v62, v62
	v_mul_f32_e32 v58, v58, v58
	v_mul_f32_e32 v59, v59, v59
	v_mul_f32_e32 v61, v61, v68
	v_mul_f32_e32 v60, v60, v60
	v_max_f32_e32 v61, 0, v61
	v_cvt_pk_bf16_f32 v58, v62, v58
	v_cvt_pk_bf16_f32 v59, v59, v60
	v_cvt_pk_bf16_f32 v60, v69, v63
	v_lshl_add_u64 v[62:63], s[26:27], 0, v[66:67]
	v_mul_f32_e32 v50, v50, v68
	v_mul_f32_e32 v51, v51, v68
	v_mul_f32_e32 v52, v52, v68
	v_mul_f32_e32 v61, v61, v61
	v_lshl_add_u64 v[62:63], v[62:63], 0, v[126:127]
	v_max_f32_e32 v50, 0, v50
	v_max_f32_e32 v51, 0, v51
	v_max_f32_e32 v52, 0, v52
	v_cvt_pk_bf16_f32 v61, v64, v61
	global_store_dwordx4 v[62:63], v[58:61], off nt
	v_mul_f32_e32 v53, v53, v68
	v_mul_f32_e32 v54, v54, v68
	v_mul_f32_e32 v58, v50, v50
	v_mul_f32_e32 v50, v55, v68
	v_mul_f32_e32 v55, v51, v51
	v_mul_f32_e32 v51, v56, v68
	v_mul_f32_e32 v56, v52, v52
	v_mul_f32_e32 v52, v57, v68
	v_max_f32_e32 v50, 0, v50
	v_max_f32_e32 v51, 0, v51
	v_max_f32_e32 v52, 0, v52
	v_max_f32_e32 v53, 0, v53
	v_max_f32_e32 v54, 0, v54
	v_mul_f32_e32 v50, v50, v50
	v_mul_f32_e32 v51, v51, v51
	v_mul_f32_e32 v52, v52, v52
	v_mul_f32_e32 v53, v53, v53
	v_mul_f32_e32 v54, v54, v54
	v_cvt_pk_bf16_f32 v50, v54, v50
	v_cvt_pk_bf16_f32 v51, v51, v52
	v_cvt_pk_bf16_f32 v52, v58, v55
	v_cvt_pk_bf16_f32 v53, v56, v53
	global_store_dwordx4 v[62:63], v[50:53], off offset:256 nt
	v_add_u32_e32 v62, 0x90, v146
	v_ashrrev_i32_e32 v63, 31, v62
	v_lshlrev_b64 v[50:51], 6, v[62:63]
	v_lshl_add_u64 v[64:65], s[54:55], 0, v[50:51]
	global_load_dwordx4 v[50:53], v[64:65], off offset:48
	global_load_dwordx4 v[54:57], v[64:65], off offset:16
	global_load_dwordx4 v[58:61], v[64:65], off offset:32
	s_nop 0
	global_load_dwordx4 v[64:67], v[64:65], off
	s_waitcnt vmcnt(1)
; DEVI unsigned pk2(float lo, float hi) { unsigned r; asm("v_cvt_pk_bf16_f32 %0, %1, %2" : "=v"(r) : "v"(lo), "v"(hi)); return r; }
;   DEVI void operator()(const f32x4 (&acc)[2][2][4][2], const pg8::Unit& u, int wr, int wc, int fr, int fq) const {
;     ...
;       for (int m = 0; m < 4; ++m) {
;         const int row = u.pm * 256 + ai * 128 + wr * 64 + m * 16 + fr;
;         const float4* sp = (const float4*)(ssrow + (size_t)row * 16);
;         const float4 a = sp[0], b = sp[1], c = sp[2], d = sp[3];
;         const float ssum = (((a.x + a.y) + (a.z + a.w)) + ((b.x + b.y) + (b.z + b.w))) + (((c.x + c.y) + (c.z + c.w)) + ((d.x + d.y) + (d.z + d.w)));
;         const float rs = rsqrtf(ssum * (1.f / 1024.f) + 1e-6f);
; #pragma unroll
;         for (int bj = 0; bj < 2; ++bj) {
;           const int col = u.pn * 256 + bj * 128 + wc * 32 + fq * 8;
;           float h[8];
; #pragma unroll
;           for (int j = 0; j < 4; ++j) { const float h0 = fmaxf(acc[ai][bj][m][0][j] * rs, 0.f), h1 = fmaxf(acc[ai][bj][m][1][j] * rs, 0.f); h[j] = h0 * h0; h[4 + j] = h1 * h1; }
;           u32x4 w; w.x = pk2(h[0], h[1]); w.y = pk2(h[2], h[3]); w.z = pk2(h[4], h[5]); w.w = pk2(h[6], h[7]);
;           *(u32x4*)(uo + (size_t)row * DFF + col) = w;
	v_mov_b32_e32 v69, v58
	s_waitcnt vmcnt(0)
	v_mov_b32_e32 v68, v64
	v_mov_b32_e32 v58, v65
	v_mov_b32_e32 v64, v66
	v_mov_b32_e32 v65, v60
	v_mov_b32_e32 v60, v67
	v_pk_add_f32 v[58:59], v[68:69], v[58:59]
	v_pk_add_f32 v[60:61], v[64:65], v[60:61]
	s_nop 0
	v_pk_add_f32 v[58:59], v[58:59], v[60:61]
	v_mov_b32_e32 v60, v54
	v_mov_b32_e32 v61, v50
	v_mov_b32_e32 v50, v55
	v_mov_b32_e32 v54, v56
	v_mov_b32_e32 v55, v52
	v_mov_b32_e32 v52, v57
	v_pk_add_f32 v[50:51], v[60:61], v[50:51]
	v_pk_add_f32 v[52:53], v[54:55], v[52:53]
	s_nop 0
	v_pk_add_f32 v[50:51], v[50:51], v[52:53]
	s_nop 0
	v_pk_add_f32 v[50:51], v[58:59], v[50:51]
	s_nop 0
	v_add_f32_e32 v50, v50, v51
	v_fmamk_f32 v50, v50, 0x3a800000, v224
	v_cmp_gt_f32_e32 vcc, s77, v50
	v_mul_f32_e32 v51, 0x4b800000, v50
	s_nop 0
	v_cndmask_b32_e32 v50, v50, v51, vcc
	v_rsq_f32_e32 v50, v50
	s_nop 0
	v_mul_f32_e32 v51, 0x45800000, v50
	v_cndmask_b32_e32 v52, v50, v51, vcc
	v_mul_f32_e32 v42, v42, v52
	v_mul_f32_e32 v43, v43, v52
	v_mul_f32_e32 v44, v44, v52
	v_max_f32_e32 v42, 0, v42
	v_max_f32_e32 v43, 0, v43
	v_max_f32_e32 v44, 0, v44
	v_mul_f32_e32 v46, v46, v52
	v_mul_f32_e32 v53, v42, v42
	v_mul_f32_e32 v42, v47, v52
	v_mul_f32_e32 v47, v43, v43
	v_mul_f32_e32 v43, v48, v52
	v_mul_f32_e32 v48, v44, v44
	v_mul_f32_e32 v44, v49, v52
	v_max_f32_e32 v46, 0, v46
	v_max_f32_e32 v42, 0, v42
	v_max_f32_e32 v43, 0, v43
	v_max_f32_e32 v44, 0, v44
	v_lshlrev_b64 v[50:51], 13, v[62:63]
	v_mul_f32_e32 v46, v46, v46
	v_mul_f32_e32 v42, v42, v42
	v_mul_f32_e32 v43, v43, v43
	v_mul_f32_e32 v45, v45, v52
	v_mul_f32_e32 v44, v44, v44
	v_max_f32_e32 v45, 0, v45
	v_cvt_pk_bf16_f32 v42, v46, v42
	v_cvt_pk_bf16_f32 v43, v43, v44
	v_cvt_pk_bf16_f32 v44, v53, v47
	v_lshl_add_u64 v[46:47], s[26:27], 0, v[50:51]
	v_mul_f32_e32 v34, v34, v52
	v_mul_f32_e32 v35, v35, v52
	v_mul_f32_e32 v36, v36, v52
	v_mul_f32_e32 v45, v45, v45
	v_lshl_add_u64 v[46:47], v[46:47], 0, v[126:127]
	v_max_f32_e32 v34, 0, v34
	v_max_f32_e32 v35, 0, v35
	v_max_f32_e32 v36, 0, v36
	v_cvt_pk_bf16_f32 v45, v48, v45
	global_store_dwordx4 v[46:47], v[42:45], off nt
	v_mul_f32_e32 v37, v37, v52
	v_mul_f32_e32 v38, v38, v52
	v_mul_f32_e32 v42, v34, v34
	v_mul_f32_e32 v34, v39, v52
	v_mul_f32_e32 v39, v35, v35
	v_mul_f32_e32 v35, v40, v52
	v_mul_f32_e32 v40, v36, v36
	v_mul_f32_e32 v36, v41, v52
	v_max_f32_e32 v34, 0, v34
	v_max_f32_e32 v35, 0, v35
	v_max_f32_e32 v36, 0, v36
	v_max_f32_e32 v37, 0, v37
	v_max_f32_e32 v38, 0, v38
	v_mul_f32_e32 v34, v34, v34
	v_mul_f32_e32 v35, v35, v35
	v_mul_f32_e32 v36, v36, v36
	v_mul_f32_e32 v37, v37, v37
	v_mul_f32_e32 v38, v38, v38
	v_cvt_pk_bf16_f32 v34, v38, v34
	v_cvt_pk_bf16_f32 v35, v35, v36
	v_cvt_pk_bf16_f32 v36, v42, v39
	v_cvt_pk_bf16_f32 v37, v40, v37
	global_store_dwordx4 v[46:47], v[34:37], off offset:256 nt
	v_add_u32_e32 v46, 0xa0, v146
	v_ashrrev_i32_e32 v47, 31, v46
	v_lshlrev_b64 v[34:35], 6, v[46:47]
	v_lshl_add_u64 v[48:49], s[54:55], 0, v[34:35]
	global_load_dwordx4 v[34:37], v[48:49], off offset:48
	global_load_dwordx4 v[38:41], v[48:49], off offset:16
	global_load_dwordx4 v[42:45], v[48:49], off offset:32
	s_nop 0
	global_load_dwordx4 v[48:51], v[48:49], off
	s_waitcnt vmcnt(1)
	v_mov_b32_e32 v53, v42
	s_waitcnt vmcnt(0)
; DEVI unsigned pk2(float lo, float hi) { unsigned r; asm("v_cvt_pk_bf16_f32 %0, %1, %2" : "=v"(r) : "v"(lo), "v"(hi)); return r; }
;   DEVI void operator()(const f32x4 (&acc)[2][2][4][2], const pg8::Unit& u, int wr, int wc, int fr, int fq) const {
; #pragma unroll
;     for (int ai = 0; ai < 2; ++ai)
; #pragma unroll
;       for (int m = 0; m < 4; ++m) {
;         const int row = u.pm * 256 + ai * 128 + wr * 64 + m * 16 + fr;
;         const float4* sp = (const float4*)(ssrow + (size_t)row * 16);
;         const float4 a = sp[0], b = sp[1], c = sp[2], d = sp[3];
;         const float ssum = (((a.x + a.y) + (a.z + a.w)) + ((b.x + b.y) + (b.z + b.w))) + (((c.x + c.y) + (c.z + c.w)) + ((d.x + d.y) + (d.z + d.w)));
;         const float rs = rsqrtf(ssum * (1.f / 1024.f) + 1e-6f);
; #pragma unroll
;         for (int bj = 0; bj < 2; ++bj) {
;           const int col = u.pn * 256 + bj * 128 + wc * 32 + fq * 8;
;           float h[8];
; #pragma unroll
;           for (int j = 0; j < 4; ++j) { const float h0 = fmaxf(acc[ai][bj][m][0][j] * rs, 0.f), h1 = fmaxf(acc[ai][bj][m][1][j] * rs, 0.f); h[j] = h0 * h0; h[4 + j] = h1 * h1; }
;           u32x4 w; w.x = pk2(h[0], h[1]); w.y = pk2(h[2], h[3]); w.z = pk2(h[4], h[5]); w.w = pk2(h[6], h[7]);
;           *(u32x4*)(uo + (size_t)row * DFF + col) = w;
;         }
;       }
;   }
	v_mov_b32_e32 v52, v48
	v_mov_b32_e32 v42, v49
	v_mov_b32_e32 v48, v50
	v_mov_b32_e32 v49, v44
	v_mov_b32_e32 v44, v51
	v_pk_add_f32 v[42:43], v[52:53], v[42:43]
	v_pk_add_f32 v[44:45], v[48:49], v[44:45]
	s_nop 0
	v_pk_add_f32 v[42:43], v[42:43], v[44:45]
	v_mov_b32_e32 v44, v38
	v_mov_b32_e32 v45, v34
	v_mov_b32_e32 v34, v39
	v_mov_b32_e32 v38, v40
	v_mov_b32_e32 v39, v36
	v_mov_b32_e32 v36, v41
	v_pk_add_f32 v[34:35], v[44:45], v[34:35]
	v_pk_add_f32 v[36:37], v[38:39], v[36:37]
	s_nop 0
	v_pk_add_f32 v[34:35], v[34:35], v[36:37]
	s_nop 0
	v_pk_add_f32 v[34:35], v[42:43], v[34:35]
	s_nop 0
	v_add_f32_e32 v34, v34, v35
	v_fmamk_f32 v34, v34, 0x3a800000, v224
	v_cmp_gt_f32_e32 vcc, s77, v34
	v_mul_f32_e32 v35, 0x4b800000, v34
	s_nop 0
	v_cndmask_b32_e32 v34, v34, v35, vcc
	v_rsq_f32_e32 v34, v34
	s_nop 0
	v_mul_f32_e32 v35, 0x45800000, v34
	v_cndmask_b32_e32 v36, v34, v35, vcc
	v_mul_f32_e32 v24, v24, v36
	v_mul_f32_e32 v25, v25, v36
	v_mul_f32_e32 v26, v26, v36
	v_max_f32_e32 v24, 0, v24
	v_max_f32_e32 v25, 0, v25
	v_max_f32_e32 v26, 0, v26
	v_mul_f32_e32 v28, v28, v36
	v_mul_f32_e32 v37, v24, v24
	v_mul_f32_e32 v24, v29, v36
	v_mul_f32_e32 v29, v25, v25
	v_mul_f32_e32 v25, v30, v36
	v_mul_f32_e32 v30, v26, v26
	v_mul_f32_e32 v26, v31, v36
	v_max_f32_e32 v28, 0, v28
	v_max_f32_e32 v24, 0, v24
	v_max_f32_e32 v25, 0, v25
	v_max_f32_e32 v26, 0, v26
	v_lshlrev_b64 v[34:35], 13, v[46:47]
	v_mul_f32_e32 v28, v28, v28
	v_mul_f32_e32 v24, v24, v24
	v_mul_f32_e32 v25, v25, v25
	v_mul_f32_e32 v27, v27, v36
	v_mul_f32_e32 v26, v26, v26
	v_max_f32_e32 v27, 0, v27
	v_cvt_pk_bf16_f32 v24, v28, v24
	v_cvt_pk_bf16_f32 v25, v25, v26
	v_cvt_pk_bf16_f32 v26, v37, v29
	v_lshl_add_u64 v[28:29], s[26:27], 0, v[34:35]
	v_mul_f32_e32 v16, v16, v36
	v_mul_f32_e32 v17, v17, v36
	v_mul_f32_e32 v18, v18, v36
	v_mul_f32_e32 v27, v27, v27
	v_lshl_add_u64 v[28:29], v[28:29], 0, v[126:127]
	v_max_f32_e32 v16, 0, v16
	v_max_f32_e32 v17, 0, v17
	v_max_f32_e32 v18, 0, v18
	v_cvt_pk_bf16_f32 v27, v30, v27
	global_store_dwordx4 v[28:29], v[24:27], off nt
	v_mul_f32_e32 v19, v19, v36
	v_mul_f32_e32 v20, v20, v36
	v_mul_f32_e32 v24, v16, v16
	v_mul_f32_e32 v16, v21, v36
	v_mul_f32_e32 v21, v17, v17
	v_mul_f32_e32 v17, v22, v36
	v_mul_f32_e32 v22, v18, v18
	v_mul_f32_e32 v18, v23, v36
	v_max_f32_e32 v16, 0, v16
	v_max_f32_e32 v17, 0, v17
	v_max_f32_e32 v18, 0, v18
	v_max_f32_e32 v19, 0, v19
	v_max_f32_e32 v20, 0, v20
	v_mul_f32_e32 v16, v16, v16
	v_mul_f32_e32 v17, v17, v17
	v_mul_f32_e32 v18, v18, v18
	v_mul_f32_e32 v19, v19, v19
	v_mul_f32_e32 v20, v20, v20
	v_cvt_pk_bf16_f32 v16, v20, v16
	v_cvt_pk_bf16_f32 v17, v17, v18
	v_cvt_pk_bf16_f32 v18, v24, v21
	v_cvt_pk_bf16_f32 v19, v22, v19
	global_store_dwordx4 v[28:29], v[16:19], off offset:256 nt
	v_add_u32_e32 v28, 0xb0, v146
	v_ashrrev_i32_e32 v29, 31, v28
	v_lshlrev_b64 v[16:17], 6, v[28:29]
	v_lshl_add_u64 v[30:31], s[54:55], 0, v[16:17]
	global_load_dwordx4 v[16:19], v[30:31], off offset:48
	global_load_dwordx4 v[20:23], v[30:31], off offset:16
	global_load_dwordx4 v[24:27], v[30:31], off offset:32
	global_load_dwordx4 v[34:37], v[30:31], off
	s_waitcnt vmcnt(1)
	v_mov_b32_e32 v31, v24
	s_waitcnt vmcnt(0)
	v_mov_b32_e32 v30, v34
	v_mov_b32_e32 v24, v35
	v_pk_add_f32 v[24:25], v[30:31], v[24:25]
	v_mov_b32_e32 v30, v36
	v_mov_b32_e32 v31, v26
	v_mov_b32_e32 v26, v37
	v_pk_add_f32 v[26:27], v[30:31], v[26:27]
	s_nop 0
	v_pk_add_f32 v[24:25], v[24:25], v[26:27]
	v_mov_b32_e32 v26, v20
	v_mov_b32_e32 v27, v16
	v_mov_b32_e32 v16, v21
	v_mov_b32_e32 v20, v22
	v_mov_b32_e32 v21, v18
	v_mov_b32_e32 v18, v23
	v_pk_add_f32 v[16:17], v[26:27], v[16:17]
	v_pk_add_f32 v[18:19], v[20:21], v[18:19]
	s_nop 0
	v_pk_add_f32 v[16:17], v[16:17], v[18:19]
	s_nop 0
	v_pk_add_f32 v[16:17], v[24:25], v[16:17]
	s_nop 0
	v_add_f32_e32 v16, v16, v17
	v_fmamk_f32 v16, v16, 0x3a800000, v224
	v_cmp_gt_f32_e32 vcc, s77, v16
	v_mul_f32_e32 v17, 0x4b800000, v16
	s_nop 0
	v_cndmask_b32_e32 v16, v16, v17, vcc
	v_rsq_f32_e32 v16, v16
	s_nop 0
	v_mul_f32_e32 v17, 0x45800000, v16
	v_cndmask_b32_e32 v18, v16, v17, vcc
	v_mul_f32_e32 v8, v8, v18
	v_mul_f32_e32 v9, v9, v18
	v_mul_f32_e32 v10, v10, v18
	v_max_f32_e32 v8, 0, v8
	v_max_f32_e32 v9, 0, v9
	v_max_f32_e32 v10, 0, v10
	v_mul_f32_e32 v12, v12, v18
	v_mul_f32_e32 v19, v8, v8
	v_mul_f32_e32 v8, v13, v18
	v_mul_f32_e32 v13, v9, v9
	v_mul_f32_e32 v9, v14, v18
	v_mul_f32_e32 v14, v10, v10
	v_mul_f32_e32 v10, v15, v18
	v_max_f32_e32 v12, 0, v12
	v_max_f32_e32 v8, 0, v8
	v_max_f32_e32 v9, 0, v9
	v_max_f32_e32 v10, 0, v10
	v_lshlrev_b64 v[16:17], 13, v[28:29]
	v_mul_f32_e32 v12, v12, v12
	v_mul_f32_e32 v8, v8, v8
	v_mul_f32_e32 v9, v9, v9
	v_mul_f32_e32 v11, v11, v18
	v_mul_f32_e32 v10, v10, v10
	v_max_f32_e32 v11, 0, v11
	v_cvt_pk_bf16_f32 v8, v12, v8
	v_cvt_pk_bf16_f32 v9, v9, v10
	v_cvt_pk_bf16_f32 v10, v19, v13
	v_lshl_add_u64 v[12:13], s[26:27], 0, v[16:17]
	v_mul_f32_e32 v0, v0, v18
	v_mul_f32_e32 v1, v1, v18
	v_mul_f32_e32 v2, v2, v18
	v_mul_f32_e32 v11, v11, v11
	v_lshl_add_u64 v[12:13], v[12:13], 0, v[126:127]
	v_max_f32_e32 v0, 0, v0
	v_max_f32_e32 v1, 0, v1
	v_max_f32_e32 v2, 0, v2
	v_cvt_pk_bf16_f32 v11, v14, v11
	global_store_dwordx4 v[12:13], v[8:11], off nt
	v_mul_f32_e32 v3, v3, v18
	v_mul_f32_e32 v4, v4, v18
	v_mul_f32_e32 v8, v0, v0
	v_mul_f32_e32 v0, v5, v18
	v_mul_f32_e32 v5, v1, v1
	v_mul_f32_e32 v1, v6, v18
	v_mul_f32_e32 v6, v2, v2
	v_mul_f32_e32 v2, v7, v18
	v_max_f32_e32 v0, 0, v0
	v_max_f32_e32 v1, 0, v1
	v_max_f32_e32 v2, 0, v2
	v_max_f32_e32 v3, 0, v3
	v_max_f32_e32 v4, 0, v4
	v_mul_f32_e32 v0, v0, v0
	v_mul_f32_e32 v1, v1, v1
	v_mul_f32_e32 v2, v2, v2
	v_mul_f32_e32 v3, v3, v3
	s_andn2_b64 vcc, exec, s[4:5]
	v_mul_f32_e32 v4, v4, v4
	v_cvt_pk_bf16_f32 v0, v4, v0
	v_cvt_pk_bf16_f32 v1, v1, v2
	v_cvt_pk_bf16_f32 v2, v8, v5
	v_cvt_pk_bf16_f32 v3, v6, v3
	global_store_dwordx4 v[12:13], v[0:3], off offset:256 nt
	s_cbranch_vccnz .LBB0_1963
	s_andn2_b64 vcc, exec, s[6:7]
	s_cbranch_vccnz .LBB0_1962
	s_barrier
	s_branch .LBB0_1962
